# final_ln layer0: batch the 8 expert-output gather loads per pair (one wait instead of four)
# speedup vs baseline: 1.0064x; 1.0064x over previous
.LBB0_1307:
	s_or_b64 exec, exec, s[16:17]
	v_lshlrev_b64 v[130:131], 12, v[130:131]
	v_lshl_add_u64 v[138:139], v[88:89], 0, v[130:131]
	v_lshlrev_b64 v[128:129], 12, v[128:129]
	v_lshl_add_u64 v[140:141], v[88:89], 0, v[128:129]
	global_load_dwordx4 v[128:131], v[138:139], off
	global_load_dwordx4 v[134:137], v[140:141], off
	global_load_dwordx4 v[142:145], v[138:139], off offset:1024
	global_load_dwordx4 v[146:149], v[140:141], off offset:1024
	global_load_dwordx4 v[150:153], v[138:139], off offset:2048
	global_load_dwordx4 v[154:157], v[140:141], off offset:2048
	global_load_dwordx4 v[158:161], v[138:139], off offset:3072
	global_load_dwordx4 v[162:165], v[140:141], off offset:3072
	s_add_i32 s19, s19, 2
	v_cmp_ge_i32_e64 s[4:5], s19, v95
	s_or_b64 s[10:11], s[4:5], s[10:11]
	s_waitcnt vmcnt(0)
	v_pk_mul_f32 v[134:135], v[126:127], v[134:135] op_sel_hi:[0,1]
	v_pk_fma_f32 v[128:129], v[124:125], v[128:129], v[134:135] op_sel_hi:[0,1,1]
	v_pk_add_f32 v[118:119], v[118:119], v[128:129]
	v_pk_mul_f32 v[128:129], v[126:127], v[136:137] op_sel_hi:[0,1]
	v_pk_fma_f32 v[128:129], v[124:125], v[130:131], v[128:129] op_sel_hi:[0,1,1]
	v_pk_add_f32 v[116:117], v[116:117], v[128:129]
	v_pk_mul_f32 v[134:135], v[126:127], v[146:147] op_sel_hi:[0,1]
	v_pk_fma_f32 v[128:129], v[124:125], v[142:143], v[134:135] op_sel_hi:[0,1,1]
	v_pk_add_f32 v[114:115], v[114:115], v[128:129]
	v_pk_mul_f32 v[128:129], v[126:127], v[148:149] op_sel_hi:[0,1]
	v_pk_fma_f32 v[128:129], v[124:125], v[144:145], v[128:129] op_sel_hi:[0,1,1]
	v_pk_add_f32 v[112:113], v[112:113], v[128:129]
	v_pk_mul_f32 v[134:135], v[126:127], v[154:155] op_sel_hi:[0,1]
	v_pk_fma_f32 v[128:129], v[124:125], v[150:151], v[134:135] op_sel_hi:[0,1,1]
	v_pk_add_f32 v[110:111], v[110:111], v[128:129]
	v_pk_mul_f32 v[128:129], v[126:127], v[156:157] op_sel_hi:[0,1]
	v_pk_fma_f32 v[128:129], v[124:125], v[152:153], v[128:129] op_sel_hi:[0,1,1]
	v_pk_add_f32 v[108:109], v[108:109], v[128:129]
	v_pk_mul_f32 v[134:135], v[126:127], v[162:163] op_sel_hi:[0,1]
	v_pk_fma_f32 v[128:129], v[124:125], v[158:159], v[134:135] op_sel_hi:[0,1,1]
	v_pk_add_f32 v[106:107], v[106:107], v[128:129]
	v_pk_mul_f32 v[128:129], v[126:127], v[164:165] op_sel_hi:[0,1]
	v_pk_fma_f32 v[128:129], v[124:125], v[160:161], v[128:129] op_sel_hi:[0,1,1]
	v_pk_add_f32 v[104:105], v[104:105], v[128:129]
	s_andn2_b64 exec, exec, s[10:11]
	s_cbranch_execz .LBB0_1301
